# hand-written gated out-projection epilogue: gate loads pipelined 16 deep
# speedup vs baseline: 1.0652x; 1.0058x over previous
;     DI void operator()(Acc& acc, const Unit& u, int wr, int wc, int fr, int fq) const {
;         const bf16_t* gate = (const bf16_t*)(F.ws + WS_GATE); bf16_t* Y = (bf16_t*)(F.ws + WS_HB);
;         const int row0 = u.pm * 256, col0 = u.pn * 256;
;         const int s1 = u.seg < 2 ? u.seg + 1 : u.seg;
; #pragma unroll
;         for (int aim = 0; aim < 4; ++aim) { const int ai = aim >> 1, mb = (aim & 1) * 2;
;             u32x4 ga[4][2], gb[4][2];
; #pragma unroll
;             for (int m = mb; m < mb + 2; ++m)
; #pragma unroll
;                 for (int bj = 0; bj < 2; ++bj) { const size_t o = (size_t)(row0 + EPI_ROWS(ai, m)) * 3072 + col0 + EPI_COL8(bj);
;                     ga[m][bj] = *(const u32x4*)(gate + o + u.seg * 1024); if (u.seg < 2) gb[m][bj] = *(const u32x4*)(gate + o + s1 * 1024); }
; #pragma unroll
;             for (int m = mb; m < mb + 2; ++m) { const int r = row0 + EPI_ROWS(ai, m);
; #pragma unroll
;                 for (int bj = 0; bj < 2; ++bj) {
;                     float g0[8]; unpk8(ga[m][bj], g0);
;                     if (u.seg < 2) { float g1[8]; unpk8(gb[m][bj], g1);
; #pragma unroll
;                         for (int e = 0; e < 8; ++e) g0[e] = g0[e] * __builtin_amdgcn_rcpf(fmaxf(g1[e], 1e-20f)); }
; #pragma unroll
;                     for (int e = 0; e < 4; ++e) { acc[ai][bj][m][0][e] *= g0[e]; acc[ai][bj][m][1][e] *= g0[4 + e]; }
.LBB0_200:
	s_lshl_b32 s6, s10, 9
	s_lshl_b32 s7, s71, 11
	s_add_u32 s50, s81, s6
	s_addc_u32 s51, s91, 0
	s_add_u32 s50, s50, s7
	s_addc_u32 s51, s51, 0
	s_add_u32 s42, s97, s6
	s_addc_u32 s43, s14, 0
	v_lshl_add_u32 v229, s4, 8, v226
	v_mul_u32_u24_e32 v214, 0x1800, v229
	v_add_u32_e32 v214, v214, v96
	v_lshl_add_u32 v215, v229, 11, v96
	s_cmp_eq_u32 s71, 2
	s_cbranch_scc1 .Lg3e_last
	s_add_u32 s6, s50, 0x0
	s_addc_u32 s7, s51, 0
	global_load_dwordx4 v[130:133], v214, s[6:7]
	global_load_dwordx4 v[134:137], v214, s[6:7] offset:2048
	global_load_dwordx4 v[138:141], v214, s[6:7] offset:256
	global_load_dwordx4 v[142:145], v214, s[6:7] offset:2304
	s_add_u32 s6, s50, 0x18000
	s_addc_u32 s7, s51, 0
	global_load_dwordx4 v[146:149], v214, s[6:7]
	global_load_dwordx4 v[150:153], v214, s[6:7] offset:2048
	global_load_dwordx4 v[154:157], v214, s[6:7] offset:256
	global_load_dwordx4 v[158:161], v214, s[6:7] offset:2304
	s_add_u32 s6, s50, 0x30000
	s_addc_u32 s7, s51, 0
	global_load_dwordx4 v[162:165], v214, s[6:7]
	global_load_dwordx4 v[166:169], v214, s[6:7] offset:2048
	global_load_dwordx4 v[170:173], v214, s[6:7] offset:256
	global_load_dwordx4 v[174:177], v214, s[6:7] offset:2304
	s_add_u32 s6, s50, 0x48000
	s_addc_u32 s7, s51, 0
	global_load_dwordx4 v[200:203], v214, s[6:7]
	global_load_dwordx4 v[204:207], v214, s[6:7] offset:2048
	global_load_dwordx4 v[208:211], v214, s[6:7] offset:256
	global_load_dwordx4 v[230:233], v214, s[6:7] offset:2304
	s_waitcnt vmcnt(12)
	v_lshlrev_b32_e32 v234, 16, v134
	v_and_b32_e32 v235, 0xffff0000, v134
	v_lshlrev_b32_e32 v236, 16, v135
	v_and_b32_e32 v237, 0xffff0000, v135
	v_lshlrev_b32_e32 v238, 16, v136
	v_and_b32_e32 v239, 0xffff0000, v136
	v_lshlrev_b32_e32 v240, 16, v137
	v_and_b32_e32 v241, 0xffff0000, v137
	v_max_f32_e32 v234, 0x1e3ce508, v234
	v_max_f32_e32 v235, 0x1e3ce508, v235
	v_max_f32_e32 v236, 0x1e3ce508, v236
	v_max_f32_e32 v237, 0x1e3ce508, v237
	v_max_f32_e32 v238, 0x1e3ce508, v238
	v_max_f32_e32 v239, 0x1e3ce508, v239
	v_max_f32_e32 v240, 0x1e3ce508, v240
	v_max_f32_e32 v241, 0x1e3ce508, v241
	v_rcp_f32_e32 v234, v234
	v_rcp_f32_e32 v235, v235
	v_rcp_f32_e32 v236, v236
	v_rcp_f32_e32 v237, v237
	v_rcp_f32_e32 v238, v238
	v_rcp_f32_e32 v239, v239
	v_rcp_f32_e32 v240, v240
	v_rcp_f32_e32 v241, v241
	v_lshlrev_b32_e32 v134, 16, v130
	v_and_b32_e32 v135, 0xffff0000, v130
	v_lshlrev_b32_e32 v136, 16, v131
	v_and_b32_e32 v137, 0xffff0000, v131
	v_lshlrev_b32_e32 v130, 16, v132
	v_and_b32_e32 v131, 0xffff0000, v132
	v_lshlrev_b32_e32 v132, 16, v133
	v_and_b32_e32 v133, 0xffff0000, v133
	v_pk_mul_f32 v[134:135], v[234:235], v[134:135]
	v_pk_mul_f32 v[136:137], v[236:237], v[136:137]
	v_pk_mul_f32 v[130:131], v[238:239], v[130:131]
	v_pk_mul_f32 v[132:133], v[240:241], v[132:133]
	v_pk_mul_f32 v[126:127], v[126:127], v[134:135]
	v_pk_mul_f32 v[122:123], v[122:123], v[130:131]
	v_pk_mul_f32 v[128:129], v[128:129], v[136:137]
	v_pk_mul_f32 v[124:125], v[124:125], v[132:133]
	v_lshlrev_b32_e32 v234, 16, v142
	v_and_b32_e32 v235, 0xffff0000, v142
	v_lshlrev_b32_e32 v236, 16, v143
	v_and_b32_e32 v237, 0xffff0000, v143
	v_lshlrev_b32_e32 v238, 16, v144
	v_and_b32_e32 v239, 0xffff0000, v144
	v_lshlrev_b32_e32 v240, 16, v145
	v_and_b32_e32 v241, 0xffff0000, v145
	v_max_f32_e32 v234, 0x1e3ce508, v234
	v_max_f32_e32 v235, 0x1e3ce508, v235
	v_max_f32_e32 v236, 0x1e3ce508, v236
	v_max_f32_e32 v237, 0x1e3ce508, v237
	v_max_f32_e32 v238, 0x1e3ce508, v238
	v_max_f32_e32 v239, 0x1e3ce508, v239
	v_max_f32_e32 v240, 0x1e3ce508, v240
	v_max_f32_e32 v241, 0x1e3ce508, v241
	v_rcp_f32_e32 v234, v234
	v_rcp_f32_e32 v235, v235
	v_rcp_f32_e32 v236, v236
	v_rcp_f32_e32 v237, v237
	v_rcp_f32_e32 v238, v238
	v_rcp_f32_e32 v239, v239
	v_rcp_f32_e32 v240, v240
	v_rcp_f32_e32 v241, v241
	v_lshlrev_b32_e32 v142, 16, v138
	v_and_b32_e32 v143, 0xffff0000, v138
	v_lshlrev_b32_e32 v144, 16, v139
	v_and_b32_e32 v145, 0xffff0000, v139
	v_lshlrev_b32_e32 v138, 16, v140
	v_and_b32_e32 v139, 0xffff0000, v140
	v_lshlrev_b32_e32 v140, 16, v141
	v_and_b32_e32 v141, 0xffff0000, v141
	v_pk_mul_f32 v[142:143], v[234:235], v[142:143]
	v_pk_mul_f32 v[144:145], v[236:237], v[144:145]
	v_pk_mul_f32 v[138:139], v[238:239], v[138:139]
	v_pk_mul_f32 v[140:141], v[240:241], v[140:141]
	v_pk_mul_f32 v[92:93], v[92:93], v[142:143]
	v_pk_mul_f32 v[88:89], v[88:89], v[138:139]
	v_pk_mul_f32 v[94:95], v[94:95], v[144:145]
	v_pk_mul_f32 v[90:91], v[90:91], v[140:141]
	s_add_u32 s6, s50, 0xc0000
	s_addc_u32 s7, s51, 0
	global_load_dwordx4 v[130:133], v214, s[6:7]
	global_load_dwordx4 v[134:137], v214, s[6:7] offset:2048
	global_load_dwordx4 v[138:141], v214, s[6:7] offset:256
	global_load_dwordx4 v[142:145], v214, s[6:7] offset:2304
	s_waitcnt vmcnt(12)
;     DI void operator()(Acc& acc, const Unit& u, int wr, int wc, int fr, int fq) const {
;     ...
;         for (int aim = 0; aim < 4; ++aim) { const int ai = aim >> 1, mb = (aim & 1) * 2;
;             u32x4 ga[4][2], gb[4][2];
; #pragma unroll
;             for (int m = mb; m < mb + 2; ++m)
; #pragma unroll
;                 for (int bj = 0; bj < 2; ++bj) { const size_t o = (size_t)(row0 + EPI_ROWS(ai, m)) * 3072 + col0 + EPI_COL8(bj);
;                     ga[m][bj] = *(const u32x4*)(gate + o + u.seg * 1024); if (u.seg < 2) gb[m][bj] = *(const u32x4*)(gate + o + s1 * 1024); }
; #pragma unroll
;             for (int m = mb; m < mb + 2; ++m) { const int r = row0 + EPI_ROWS(ai, m);
; #pragma unroll
;                 for (int bj = 0; bj < 2; ++bj) {
;                     float g0[8]; unpk8(ga[m][bj], g0);
;                     if (u.seg < 2) { float g1[8]; unpk8(gb[m][bj], g1);
; #pragma unroll
;                         for (int e = 0; e < 8; ++e) g0[e] = g0[e] * __builtin_amdgcn_rcpf(fmaxf(g1[e], 1e-20f)); }
; #pragma unroll
;                     for (int e = 0; e < 4; ++e) { acc[ai][bj][m][0][e] *= g0[e]; acc[ai][bj][m][1][e] *= g0[4 + e]; }
	v_lshlrev_b32_e32 v234, 16, v150
	v_and_b32_e32 v235, 0xffff0000, v150
	v_lshlrev_b32_e32 v236, 16, v151
	v_and_b32_e32 v237, 0xffff0000, v151
	v_lshlrev_b32_e32 v238, 16, v152
	v_and_b32_e32 v239, 0xffff0000, v152
	v_lshlrev_b32_e32 v240, 16, v153
	v_and_b32_e32 v241, 0xffff0000, v153
	v_max_f32_e32 v234, 0x1e3ce508, v234
	v_max_f32_e32 v235, 0x1e3ce508, v235
	v_max_f32_e32 v236, 0x1e3ce508, v236
	v_max_f32_e32 v237, 0x1e3ce508, v237
	v_max_f32_e32 v238, 0x1e3ce508, v238
	v_max_f32_e32 v239, 0x1e3ce508, v239
	v_max_f32_e32 v240, 0x1e3ce508, v240
	v_max_f32_e32 v241, 0x1e3ce508, v241
	v_rcp_f32_e32 v234, v234
	v_rcp_f32_e32 v235, v235
	v_rcp_f32_e32 v236, v236
	v_rcp_f32_e32 v237, v237
	v_rcp_f32_e32 v238, v238
	v_rcp_f32_e32 v239, v239
	v_rcp_f32_e32 v240, v240
	v_rcp_f32_e32 v241, v241
	v_lshlrev_b32_e32 v150, 16, v146
	v_and_b32_e32 v151, 0xffff0000, v146
	v_lshlrev_b32_e32 v152, 16, v147
	v_and_b32_e32 v153, 0xffff0000, v147
	v_lshlrev_b32_e32 v146, 16, v148
	v_and_b32_e32 v147, 0xffff0000, v148
	v_lshlrev_b32_e32 v148, 16, v149
	v_and_b32_e32 v149, 0xffff0000, v149
	v_pk_mul_f32 v[150:151], v[234:235], v[150:151]
	v_pk_mul_f32 v[152:153], v[236:237], v[152:153]
	v_pk_mul_f32 v[146:147], v[238:239], v[146:147]
	v_pk_mul_f32 v[148:149], v[240:241], v[148:149]
	v_pk_mul_f32 v[118:119], v[118:119], v[150:151]
	v_pk_mul_f32 v[114:115], v[114:115], v[146:147]
	v_pk_mul_f32 v[120:121], v[120:121], v[152:153]
	v_pk_mul_f32 v[116:117], v[116:117], v[148:149]
	v_lshlrev_b32_e32 v234, 16, v158
	v_and_b32_e32 v235, 0xffff0000, v158
	v_lshlrev_b32_e32 v236, 16, v159
	v_and_b32_e32 v237, 0xffff0000, v159
	v_lshlrev_b32_e32 v238, 16, v160
	v_and_b32_e32 v239, 0xffff0000, v160
	v_lshlrev_b32_e32 v240, 16, v161
	v_and_b32_e32 v241, 0xffff0000, v161
	v_max_f32_e32 v234, 0x1e3ce508, v234
	v_max_f32_e32 v235, 0x1e3ce508, v235
	v_max_f32_e32 v236, 0x1e3ce508, v236
	v_max_f32_e32 v237, 0x1e3ce508, v237
	v_max_f32_e32 v238, 0x1e3ce508, v238
	v_max_f32_e32 v239, 0x1e3ce508, v239
	v_max_f32_e32 v240, 0x1e3ce508, v240
	v_max_f32_e32 v241, 0x1e3ce508, v241
	v_rcp_f32_e32 v234, v234
	v_rcp_f32_e32 v235, v235
	v_rcp_f32_e32 v236, v236
	v_rcp_f32_e32 v237, v237
	v_rcp_f32_e32 v238, v238
	v_rcp_f32_e32 v239, v239
	v_rcp_f32_e32 v240, v240
	v_rcp_f32_e32 v241, v241
	v_lshlrev_b32_e32 v158, 16, v154
	v_and_b32_e32 v159, 0xffff0000, v154
	v_lshlrev_b32_e32 v160, 16, v155
	v_and_b32_e32 v161, 0xffff0000, v155
	v_lshlrev_b32_e32 v154, 16, v156
	v_and_b32_e32 v155, 0xffff0000, v156
	v_lshlrev_b32_e32 v156, 16, v157
	v_and_b32_e32 v157, 0xffff0000, v157
	v_pk_mul_f32 v[158:159], v[234:235], v[158:159]
	v_pk_mul_f32 v[160:161], v[236:237], v[160:161]
	v_pk_mul_f32 v[154:155], v[238:239], v[154:155]
	v_pk_mul_f32 v[156:157], v[240:241], v[156:157]
	v_pk_mul_f32 v[84:85], v[84:85], v[158:159]
	v_pk_mul_f32 v[80:81], v[80:81], v[154:155]
	v_pk_mul_f32 v[86:87], v[86:87], v[160:161]
	v_pk_mul_f32 v[82:83], v[82:83], v[156:157]
	s_add_u32 s6, s50, 0xd8000
	s_addc_u32 s7, s51, 0
	global_load_dwordx4 v[146:149], v214, s[6:7]
	global_load_dwordx4 v[150:153], v214, s[6:7] offset:2048
	global_load_dwordx4 v[154:157], v214, s[6:7] offset:256
	global_load_dwordx4 v[158:161], v214, s[6:7] offset:2304
	s_waitcnt vmcnt(12)
	v_lshlrev_b32_e32 v234, 16, v166
	v_and_b32_e32 v235, 0xffff0000, v166
	v_lshlrev_b32_e32 v236, 16, v167
	v_and_b32_e32 v237, 0xffff0000, v167
	v_lshlrev_b32_e32 v238, 16, v168
	v_and_b32_e32 v239, 0xffff0000, v168
	v_lshlrev_b32_e32 v240, 16, v169
	v_and_b32_e32 v241, 0xffff0000, v169
	v_max_f32_e32 v234, 0x1e3ce508, v234
	v_max_f32_e32 v235, 0x1e3ce508, v235
	v_max_f32_e32 v236, 0x1e3ce508, v236
	v_max_f32_e32 v237, 0x1e3ce508, v237
	v_max_f32_e32 v238, 0x1e3ce508, v238
	v_max_f32_e32 v239, 0x1e3ce508, v239
	v_max_f32_e32 v240, 0x1e3ce508, v240
	v_max_f32_e32 v241, 0x1e3ce508, v241
	v_rcp_f32_e32 v234, v234
	v_rcp_f32_e32 v235, v235
	v_rcp_f32_e32 v236, v236
	v_rcp_f32_e32 v237, v237
	v_rcp_f32_e32 v238, v238
	v_rcp_f32_e32 v239, v239
	v_rcp_f32_e32 v240, v240
	v_rcp_f32_e32 v241, v241
	v_lshlrev_b32_e32 v166, 16, v162
	v_and_b32_e32 v167, 0xffff0000, v162
	v_lshlrev_b32_e32 v168, 16, v163
	v_and_b32_e32 v169, 0xffff0000, v163
	v_lshlrev_b32_e32 v162, 16, v164
	v_and_b32_e32 v163, 0xffff0000, v164
	v_lshlrev_b32_e32 v164, 16, v165
	v_and_b32_e32 v165, 0xffff0000, v165
	v_pk_mul_f32 v[166:167], v[234:235], v[166:167]
	v_pk_mul_f32 v[168:169], v[236:237], v[168:169]
	v_pk_mul_f32 v[162:163], v[238:239], v[162:163]
	v_pk_mul_f32 v[164:165], v[240:241], v[164:165]
	v_pk_mul_f32 v[110:111], v[110:111], v[166:167]
	v_pk_mul_f32 v[106:107], v[106:107], v[162:163]
	v_pk_mul_f32 v[112:113], v[112:113], v[168:169]
	v_pk_mul_f32 v[108:109], v[108:109], v[164:165]
	v_lshlrev_b32_e32 v234, 16, v174
	v_and_b32_e32 v235, 0xffff0000, v174
	v_lshlrev_b32_e32 v236, 16, v175
	v_and_b32_e32 v237, 0xffff0000, v175
	v_lshlrev_b32_e32 v238, 16, v176
	v_and_b32_e32 v239, 0xffff0000, v176
	v_lshlrev_b32_e32 v240, 16, v177
	v_and_b32_e32 v241, 0xffff0000, v177
	v_max_f32_e32 v234, 0x1e3ce508, v234
	v_max_f32_e32 v235, 0x1e3ce508, v235
	v_max_f32_e32 v236, 0x1e3ce508, v236
	v_max_f32_e32 v237, 0x1e3ce508, v237
	v_max_f32_e32 v238, 0x1e3ce508, v238
	v_max_f32_e32 v239, 0x1e3ce508, v239
	v_max_f32_e32 v240, 0x1e3ce508, v240
	v_max_f32_e32 v241, 0x1e3ce508, v241
	v_rcp_f32_e32 v234, v234
	v_rcp_f32_e32 v235, v235
	v_rcp_f32_e32 v236, v236
	v_rcp_f32_e32 v237, v237
	v_rcp_f32_e32 v238, v238
	v_rcp_f32_e32 v239, v239
	v_rcp_f32_e32 v240, v240
	v_rcp_f32_e32 v241, v241
	v_lshlrev_b32_e32 v174, 16, v170
	v_and_b32_e32 v175, 0xffff0000, v170
	v_lshlrev_b32_e32 v176, 16, v171
	v_and_b32_e32 v177, 0xffff0000, v171
	v_lshlrev_b32_e32 v170, 16, v172
	v_and_b32_e32 v171, 0xffff0000, v172
	v_lshlrev_b32_e32 v172, 16, v173
	v_and_b32_e32 v173, 0xffff0000, v173
	v_pk_mul_f32 v[174:175], v[234:235], v[174:175]
	v_pk_mul_f32 v[176:177], v[236:237], v[176:177]
	v_pk_mul_f32 v[170:171], v[238:239], v[170:171]
	v_pk_mul_f32 v[172:173], v[240:241], v[172:173]
	v_pk_mul_f32 v[76:77], v[76:77], v[174:175]
	v_pk_mul_f32 v[72:73], v[72:73], v[170:171]
	v_pk_mul_f32 v[78:79], v[78:79], v[176:177]
	v_pk_mul_f32 v[74:75], v[74:75], v[172:173]
	s_add_u32 s6, s50, 0xf0000
	s_addc_u32 s7, s51, 0
	global_load_dwordx4 v[162:165], v214, s[6:7]
	global_load_dwordx4 v[166:169], v214, s[6:7] offset:2048
	global_load_dwordx4 v[170:173], v214, s[6:7] offset:256
	global_load_dwordx4 v[174:177], v214, s[6:7] offset:2304
	s_waitcnt vmcnt(12)
;     DI void operator()(Acc& acc, const Unit& u, int wr, int wc, int fr, int fq) const {
;     ...
;         for (int aim = 0; aim < 4; ++aim) { const int ai = aim >> 1, mb = (aim & 1) * 2;
;             u32x4 ga[4][2], gb[4][2];
; #pragma unroll
;             for (int m = mb; m < mb + 2; ++m)
; #pragma unroll
;                 for (int bj = 0; bj < 2; ++bj) { const size_t o = (size_t)(row0 + EPI_ROWS(ai, m)) * 3072 + col0 + EPI_COL8(bj);
;                     ga[m][bj] = *(const u32x4*)(gate + o + u.seg * 1024); if (u.seg < 2) gb[m][bj] = *(const u32x4*)(gate + o + s1 * 1024); }
; #pragma unroll
;             for (int m = mb; m < mb + 2; ++m) { const int r = row0 + EPI_ROWS(ai, m);
; #pragma unroll
;                 for (int bj = 0; bj < 2; ++bj) {
;                     float g0[8]; unpk8(ga[m][bj], g0);
;                     if (u.seg < 2) { float g1[8]; unpk8(gb[m][bj], g1);
; #pragma unroll
;                         for (int e = 0; e < 8; ++e) g0[e] = g0[e] * __builtin_amdgcn_rcpf(fmaxf(g1[e], 1e-20f)); }
; #pragma unroll
;                     for (int e = 0; e < 4; ++e) { acc[ai][bj][m][0][e] *= g0[e]; acc[ai][bj][m][1][e] *= g0[4 + e]; }
	v_lshlrev_b32_e32 v234, 16, v204
	v_and_b32_e32 v235, 0xffff0000, v204
	v_lshlrev_b32_e32 v236, 16, v205
	v_and_b32_e32 v237, 0xffff0000, v205
	v_lshlrev_b32_e32 v238, 16, v206
	v_and_b32_e32 v239, 0xffff0000, v206
	v_lshlrev_b32_e32 v240, 16, v207
	v_and_b32_e32 v241, 0xffff0000, v207
	v_max_f32_e32 v234, 0x1e3ce508, v234
	v_max_f32_e32 v235, 0x1e3ce508, v235
	v_max_f32_e32 v236, 0x1e3ce508, v236
	v_max_f32_e32 v237, 0x1e3ce508, v237
	v_max_f32_e32 v238, 0x1e3ce508, v238
	v_max_f32_e32 v239, 0x1e3ce508, v239
	v_max_f32_e32 v240, 0x1e3ce508, v240
	v_max_f32_e32 v241, 0x1e3ce508, v241
	v_rcp_f32_e32 v234, v234
	v_rcp_f32_e32 v235, v235
	v_rcp_f32_e32 v236, v236
	v_rcp_f32_e32 v237, v237
	v_rcp_f32_e32 v238, v238
	v_rcp_f32_e32 v239, v239
	v_rcp_f32_e32 v240, v240
	v_rcp_f32_e32 v241, v241
	v_lshlrev_b32_e32 v204, 16, v200
	v_and_b32_e32 v205, 0xffff0000, v200
	v_lshlrev_b32_e32 v206, 16, v201
	v_and_b32_e32 v207, 0xffff0000, v201
	v_lshlrev_b32_e32 v200, 16, v202
	v_and_b32_e32 v201, 0xffff0000, v202
	v_lshlrev_b32_e32 v202, 16, v203
	v_and_b32_e32 v203, 0xffff0000, v203
	v_pk_mul_f32 v[204:205], v[234:235], v[204:205]
	v_pk_mul_f32 v[206:207], v[236:237], v[206:207]
	v_pk_mul_f32 v[200:201], v[238:239], v[200:201]
	v_pk_mul_f32 v[202:203], v[240:241], v[202:203]
	v_pk_mul_f32 v[102:103], v[102:103], v[204:205]
	v_pk_mul_f32 v[98:99], v[98:99], v[200:201]
	v_pk_mul_f32 v[104:105], v[104:105], v[206:207]
	v_pk_mul_f32 v[100:101], v[100:101], v[202:203]
	v_lshlrev_b32_e32 v234, 16, v230
	v_and_b32_e32 v235, 0xffff0000, v230
	v_lshlrev_b32_e32 v236, 16, v231
	v_and_b32_e32 v237, 0xffff0000, v231
	v_lshlrev_b32_e32 v238, 16, v232
	v_and_b32_e32 v239, 0xffff0000, v232
	v_lshlrev_b32_e32 v240, 16, v233
	v_and_b32_e32 v241, 0xffff0000, v233
	v_max_f32_e32 v234, 0x1e3ce508, v234
	v_max_f32_e32 v235, 0x1e3ce508, v235
	v_max_f32_e32 v236, 0x1e3ce508, v236
	v_max_f32_e32 v237, 0x1e3ce508, v237
	v_max_f32_e32 v238, 0x1e3ce508, v238
	v_max_f32_e32 v239, 0x1e3ce508, v239
	v_max_f32_e32 v240, 0x1e3ce508, v240
	v_max_f32_e32 v241, 0x1e3ce508, v241
	v_rcp_f32_e32 v234, v234
	v_rcp_f32_e32 v235, v235
	v_rcp_f32_e32 v236, v236
	v_rcp_f32_e32 v237, v237
	v_rcp_f32_e32 v238, v238
	v_rcp_f32_e32 v239, v239
	v_rcp_f32_e32 v240, v240
	v_rcp_f32_e32 v241, v241
	v_lshlrev_b32_e32 v230, 16, v208
	v_and_b32_e32 v231, 0xffff0000, v208
	v_lshlrev_b32_e32 v232, 16, v209
	v_and_b32_e32 v233, 0xffff0000, v209
	v_lshlrev_b32_e32 v208, 16, v210
	v_and_b32_e32 v209, 0xffff0000, v210
	v_lshlrev_b32_e32 v210, 16, v211
	v_and_b32_e32 v211, 0xffff0000, v211
	v_pk_mul_f32 v[230:231], v[234:235], v[230:231]
	v_pk_mul_f32 v[232:233], v[236:237], v[232:233]
	v_pk_mul_f32 v[208:209], v[238:239], v[208:209]
	v_pk_mul_f32 v[210:211], v[240:241], v[210:211]
	v_pk_mul_f32 v[68:69], v[68:69], v[230:231]
	v_pk_mul_f32 v[64:65], v[64:65], v[208:209]
	v_pk_mul_f32 v[70:71], v[70:71], v[232:233]
	v_pk_mul_f32 v[66:67], v[66:67], v[210:211]
	s_add_u32 s6, s50, 0x108000
	s_addc_u32 s7, s51, 0
	global_load_dwordx4 v[200:203], v214, s[6:7]
	global_load_dwordx4 v[204:207], v214, s[6:7] offset:2048
	global_load_dwordx4 v[208:211], v214, s[6:7] offset:256
	global_load_dwordx4 v[230:233], v214, s[6:7] offset:2304
	s_waitcnt vmcnt(12)
	v_lshlrev_b32_e32 v234, 16, v134
	v_and_b32_e32 v235, 0xffff0000, v134
	v_lshlrev_b32_e32 v236, 16, v135
	v_and_b32_e32 v237, 0xffff0000, v135
	v_lshlrev_b32_e32 v238, 16, v136
	v_and_b32_e32 v239, 0xffff0000, v136
	v_lshlrev_b32_e32 v240, 16, v137
	v_and_b32_e32 v241, 0xffff0000, v137
	v_max_f32_e32 v234, 0x1e3ce508, v234
	v_max_f32_e32 v235, 0x1e3ce508, v235
	v_max_f32_e32 v236, 0x1e3ce508, v236
	v_max_f32_e32 v237, 0x1e3ce508, v237
	v_max_f32_e32 v238, 0x1e3ce508, v238
	v_max_f32_e32 v239, 0x1e3ce508, v239
	v_max_f32_e32 v240, 0x1e3ce508, v240
	v_max_f32_e32 v241, 0x1e3ce508, v241
	v_rcp_f32_e32 v234, v234
	v_rcp_f32_e32 v235, v235
	v_rcp_f32_e32 v236, v236
	v_rcp_f32_e32 v237, v237
	v_rcp_f32_e32 v238, v238
	v_rcp_f32_e32 v239, v239
	v_rcp_f32_e32 v240, v240
	v_rcp_f32_e32 v241, v241
	v_lshlrev_b32_e32 v134, 16, v130
	v_and_b32_e32 v135, 0xffff0000, v130
	v_lshlrev_b32_e32 v136, 16, v131
	v_and_b32_e32 v137, 0xffff0000, v131
	v_lshlrev_b32_e32 v130, 16, v132
	v_and_b32_e32 v131, 0xffff0000, v132
	v_lshlrev_b32_e32 v132, 16, v133
	v_and_b32_e32 v133, 0xffff0000, v133
	v_pk_mul_f32 v[134:135], v[234:235], v[134:135]
	v_pk_mul_f32 v[136:137], v[236:237], v[136:137]
	v_pk_mul_f32 v[130:131], v[238:239], v[130:131]
	v_pk_mul_f32 v[132:133], v[240:241], v[132:133]
	v_pk_mul_f32 v[60:61], v[60:61], v[134:135]
	v_pk_mul_f32 v[56:57], v[56:57], v[130:131]
	v_pk_mul_f32 v[62:63], v[62:63], v[136:137]
	v_pk_mul_f32 v[58:59], v[58:59], v[132:133]
	v_lshlrev_b32_e32 v234, 16, v142
	v_and_b32_e32 v235, 0xffff0000, v142
	v_lshlrev_b32_e32 v236, 16, v143
	v_and_b32_e32 v237, 0xffff0000, v143
	v_lshlrev_b32_e32 v238, 16, v144
	v_and_b32_e32 v239, 0xffff0000, v144
	v_lshlrev_b32_e32 v240, 16, v145
	v_and_b32_e32 v241, 0xffff0000, v145
	v_max_f32_e32 v234, 0x1e3ce508, v234
	v_max_f32_e32 v235, 0x1e3ce508, v235
	v_max_f32_e32 v236, 0x1e3ce508, v236
	v_max_f32_e32 v237, 0x1e3ce508, v237
	v_max_f32_e32 v238, 0x1e3ce508, v238
	v_max_f32_e32 v239, 0x1e3ce508, v239
	v_max_f32_e32 v240, 0x1e3ce508, v240
	v_max_f32_e32 v241, 0x1e3ce508, v241
	v_rcp_f32_e32 v234, v234
	v_rcp_f32_e32 v235, v235
	v_rcp_f32_e32 v236, v236
	v_rcp_f32_e32 v237, v237
	v_rcp_f32_e32 v238, v238
	v_rcp_f32_e32 v239, v239
	v_rcp_f32_e32 v240, v240
	v_rcp_f32_e32 v241, v241
	v_lshlrev_b32_e32 v142, 16, v138
	v_and_b32_e32 v143, 0xffff0000, v138
	v_lshlrev_b32_e32 v144, 16, v139
	v_and_b32_e32 v145, 0xffff0000, v139
	v_lshlrev_b32_e32 v138, 16, v140
	v_and_b32_e32 v139, 0xffff0000, v140
	v_lshlrev_b32_e32 v140, 16, v141
	v_and_b32_e32 v141, 0xffff0000, v141
	v_pk_mul_f32 v[142:143], v[234:235], v[142:143]
	v_pk_mul_f32 v[144:145], v[236:237], v[144:145]
	v_pk_mul_f32 v[138:139], v[238:239], v[138:139]
	v_pk_mul_f32 v[140:141], v[240:241], v[140:141]
	v_pk_mul_f32 v[28:29], v[28:29], v[142:143]
	v_pk_mul_f32 v[24:25], v[24:25], v[138:139]
	v_pk_mul_f32 v[30:31], v[30:31], v[144:145]
	v_pk_mul_f32 v[26:27], v[26:27], v[140:141]
	s_waitcnt vmcnt(8)
;     DI void operator()(Acc& acc, const Unit& u, int wr, int wc, int fr, int fq) const {
;     ...
;         for (int aim = 0; aim < 4; ++aim) { const int ai = aim >> 1, mb = (aim & 1) * 2;
;             u32x4 ga[4][2], gb[4][2];
; #pragma unroll
;             for (int m = mb; m < mb + 2; ++m)
; #pragma unroll
;                 for (int bj = 0; bj < 2; ++bj) { const size_t o = (size_t)(row0 + EPI_ROWS(ai, m)) * 3072 + col0 + EPI_COL8(bj);
;                     ga[m][bj] = *(const u32x4*)(gate + o + u.seg * 1024); if (u.seg < 2) gb[m][bj] = *(const u32x4*)(gate + o + s1 * 1024); }
; #pragma unroll
;             for (int m = mb; m < mb + 2; ++m) { const int r = row0 + EPI_ROWS(ai, m);
; #pragma unroll
;                 for (int bj = 0; bj < 2; ++bj) {
;                     float g0[8]; unpk8(ga[m][bj], g0);
;                     if (u.seg < 2) { float g1[8]; unpk8(gb[m][bj], g1);
; #pragma unroll
;                         for (int e = 0; e < 8; ++e) g0[e] = g0[e] * __builtin_amdgcn_rcpf(fmaxf(g1[e], 1e-20f)); }
; #pragma unroll
;                     for (int e = 0; e < 4; ++e) { acc[ai][bj][m][0][e] *= g0[e]; acc[ai][bj][m][1][e] *= g0[4 + e]; }
	v_lshlrev_b32_e32 v234, 16, v150
	v_and_b32_e32 v235, 0xffff0000, v150
	v_lshlrev_b32_e32 v236, 16, v151
	v_and_b32_e32 v237, 0xffff0000, v151
	v_lshlrev_b32_e32 v238, 16, v152
	v_and_b32_e32 v239, 0xffff0000, v152
	v_lshlrev_b32_e32 v240, 16, v153
	v_and_b32_e32 v241, 0xffff0000, v153
	v_max_f32_e32 v234, 0x1e3ce508, v234
	v_max_f32_e32 v235, 0x1e3ce508, v235
	v_max_f32_e32 v236, 0x1e3ce508, v236
	v_max_f32_e32 v237, 0x1e3ce508, v237
	v_max_f32_e32 v238, 0x1e3ce508, v238
	v_max_f32_e32 v239, 0x1e3ce508, v239
	v_max_f32_e32 v240, 0x1e3ce508, v240
	v_max_f32_e32 v241, 0x1e3ce508, v241
	v_rcp_f32_e32 v234, v234
	v_rcp_f32_e32 v235, v235
	v_rcp_f32_e32 v236, v236
	v_rcp_f32_e32 v237, v237
	v_rcp_f32_e32 v238, v238
	v_rcp_f32_e32 v239, v239
	v_rcp_f32_e32 v240, v240
	v_rcp_f32_e32 v241, v241
	v_lshlrev_b32_e32 v150, 16, v146
	v_and_b32_e32 v151, 0xffff0000, v146
	v_lshlrev_b32_e32 v152, 16, v147
	v_and_b32_e32 v153, 0xffff0000, v147
	v_lshlrev_b32_e32 v146, 16, v148
	v_and_b32_e32 v147, 0xffff0000, v148
	v_lshlrev_b32_e32 v148, 16, v149
	v_and_b32_e32 v149, 0xffff0000, v149
	v_pk_mul_f32 v[150:151], v[234:235], v[150:151]
	v_pk_mul_f32 v[152:153], v[236:237], v[152:153]
	v_pk_mul_f32 v[146:147], v[238:239], v[146:147]
	v_pk_mul_f32 v[148:149], v[240:241], v[148:149]
	v_pk_mul_f32 v[52:53], v[52:53], v[150:151]
	v_pk_mul_f32 v[48:49], v[48:49], v[146:147]
	v_pk_mul_f32 v[54:55], v[54:55], v[152:153]
	v_pk_mul_f32 v[50:51], v[50:51], v[148:149]
	v_lshlrev_b32_e32 v234, 16, v158
	v_and_b32_e32 v235, 0xffff0000, v158
	v_lshlrev_b32_e32 v236, 16, v159
	v_and_b32_e32 v237, 0xffff0000, v159
	v_lshlrev_b32_e32 v238, 16, v160
	v_and_b32_e32 v239, 0xffff0000, v160
	v_lshlrev_b32_e32 v240, 16, v161
	v_and_b32_e32 v241, 0xffff0000, v161
	v_max_f32_e32 v234, 0x1e3ce508, v234
	v_max_f32_e32 v235, 0x1e3ce508, v235
	v_max_f32_e32 v236, 0x1e3ce508, v236
	v_max_f32_e32 v237, 0x1e3ce508, v237
	v_max_f32_e32 v238, 0x1e3ce508, v238
	v_max_f32_e32 v239, 0x1e3ce508, v239
	v_max_f32_e32 v240, 0x1e3ce508, v240
	v_max_f32_e32 v241, 0x1e3ce508, v241
	v_rcp_f32_e32 v234, v234
	v_rcp_f32_e32 v235, v235
	v_rcp_f32_e32 v236, v236
	v_rcp_f32_e32 v237, v237
	v_rcp_f32_e32 v238, v238
	v_rcp_f32_e32 v239, v239
	v_rcp_f32_e32 v240, v240
	v_rcp_f32_e32 v241, v241
	v_lshlrev_b32_e32 v158, 16, v154
	v_and_b32_e32 v159, 0xffff0000, v154
	v_lshlrev_b32_e32 v160, 16, v155
	v_and_b32_e32 v161, 0xffff0000, v155
	v_lshlrev_b32_e32 v154, 16, v156
	v_and_b32_e32 v155, 0xffff0000, v156
	v_lshlrev_b32_e32 v156, 16, v157
	v_and_b32_e32 v157, 0xffff0000, v157
	v_pk_mul_f32 v[158:159], v[234:235], v[158:159]
	v_pk_mul_f32 v[160:161], v[236:237], v[160:161]
	v_pk_mul_f32 v[154:155], v[238:239], v[154:155]
	v_pk_mul_f32 v[156:157], v[240:241], v[156:157]
	v_pk_mul_f32 v[20:21], v[20:21], v[158:159]
	v_pk_mul_f32 v[16:17], v[16:17], v[154:155]
	v_pk_mul_f32 v[22:23], v[22:23], v[160:161]
	v_pk_mul_f32 v[18:19], v[18:19], v[156:157]
	s_waitcnt vmcnt(4)
	v_lshlrev_b32_e32 v234, 16, v166
	v_and_b32_e32 v235, 0xffff0000, v166
	v_lshlrev_b32_e32 v236, 16, v167
	v_and_b32_e32 v237, 0xffff0000, v167
	v_lshlrev_b32_e32 v238, 16, v168
	v_and_b32_e32 v239, 0xffff0000, v168
	v_lshlrev_b32_e32 v240, 16, v169
	v_and_b32_e32 v241, 0xffff0000, v169
	v_max_f32_e32 v234, 0x1e3ce508, v234
	v_max_f32_e32 v235, 0x1e3ce508, v235
	v_max_f32_e32 v236, 0x1e3ce508, v236
	v_max_f32_e32 v237, 0x1e3ce508, v237
	v_max_f32_e32 v238, 0x1e3ce508, v238
	v_max_f32_e32 v239, 0x1e3ce508, v239
	v_max_f32_e32 v240, 0x1e3ce508, v240
	v_max_f32_e32 v241, 0x1e3ce508, v241
	v_rcp_f32_e32 v234, v234
	v_rcp_f32_e32 v235, v235
	v_rcp_f32_e32 v236, v236
	v_rcp_f32_e32 v237, v237
	v_rcp_f32_e32 v238, v238
	v_rcp_f32_e32 v239, v239
	v_rcp_f32_e32 v240, v240
	v_rcp_f32_e32 v241, v241
	v_lshlrev_b32_e32 v166, 16, v162
	v_and_b32_e32 v167, 0xffff0000, v162
	v_lshlrev_b32_e32 v168, 16, v163
	v_and_b32_e32 v169, 0xffff0000, v163
	v_lshlrev_b32_e32 v162, 16, v164
	v_and_b32_e32 v163, 0xffff0000, v164
	v_lshlrev_b32_e32 v164, 16, v165
	v_and_b32_e32 v165, 0xffff0000, v165
	v_pk_mul_f32 v[166:167], v[234:235], v[166:167]
	v_pk_mul_f32 v[168:169], v[236:237], v[168:169]
	v_pk_mul_f32 v[162:163], v[238:239], v[162:163]
	v_pk_mul_f32 v[164:165], v[240:241], v[164:165]
	v_pk_mul_f32 v[44:45], v[44:45], v[166:167]
	v_pk_mul_f32 v[40:41], v[40:41], v[162:163]
	v_pk_mul_f32 v[46:47], v[46:47], v[168:169]
	v_pk_mul_f32 v[42:43], v[42:43], v[164:165]
	v_lshlrev_b32_e32 v234, 16, v174
	v_and_b32_e32 v235, 0xffff0000, v174
	v_lshlrev_b32_e32 v236, 16, v175
	v_and_b32_e32 v237, 0xffff0000, v175
	v_lshlrev_b32_e32 v238, 16, v176
	v_and_b32_e32 v239, 0xffff0000, v176
	v_lshlrev_b32_e32 v240, 16, v177
	v_and_b32_e32 v241, 0xffff0000, v177
	v_max_f32_e32 v234, 0x1e3ce508, v234
	v_max_f32_e32 v235, 0x1e3ce508, v235
	v_max_f32_e32 v236, 0x1e3ce508, v236
	v_max_f32_e32 v237, 0x1e3ce508, v237
	v_max_f32_e32 v238, 0x1e3ce508, v238
	v_max_f32_e32 v239, 0x1e3ce508, v239
	v_max_f32_e32 v240, 0x1e3ce508, v240
	v_max_f32_e32 v241, 0x1e3ce508, v241
	v_rcp_f32_e32 v234, v234
	v_rcp_f32_e32 v235, v235
	v_rcp_f32_e32 v236, v236
	v_rcp_f32_e32 v237, v237
	v_rcp_f32_e32 v238, v238
	v_rcp_f32_e32 v239, v239
	v_rcp_f32_e32 v240, v240
	v_rcp_f32_e32 v241, v241
	v_lshlrev_b32_e32 v174, 16, v170
	v_and_b32_e32 v175, 0xffff0000, v170
	v_lshlrev_b32_e32 v176, 16, v171
	v_and_b32_e32 v177, 0xffff0000, v171
	v_lshlrev_b32_e32 v170, 16, v172
	v_and_b32_e32 v171, 0xffff0000, v172
	v_lshlrev_b32_e32 v172, 16, v173
	v_and_b32_e32 v173, 0xffff0000, v173
	v_pk_mul_f32 v[174:175], v[234:235], v[174:175]
	v_pk_mul_f32 v[176:177], v[236:237], v[176:177]
	v_pk_mul_f32 v[170:171], v[238:239], v[170:171]
	v_pk_mul_f32 v[172:173], v[240:241], v[172:173]
	v_pk_mul_f32 v[12:13], v[12:13], v[174:175]
	v_pk_mul_f32 v[8:9], v[8:9], v[170:171]
	v_pk_mul_f32 v[14:15], v[14:15], v[176:177]
	v_pk_mul_f32 v[10:11], v[10:11], v[172:173]
	s_waitcnt vmcnt(0)
; DI u32x4 pk8(const f32x4& a, const f32x4& b) { u32x4 w; w.x = pk2(a[0], a[1]); w.y = pk2(a[2], a[3]); w.z = pk2(b[0], b[1]); w.w = pk2(b[2], b[3]); return w; }
;     DI void operator()(Acc& acc, const Unit& u, int wr, int wc, int fr, int fq) const {
;     ...
;         for (int aim = 0; aim < 4; ++aim) { const int ai = aim >> 1, mb = (aim & 1) * 2;
;             u32x4 ga[4][2], gb[4][2];
; #pragma unroll
;             for (int m = mb; m < mb + 2; ++m)
; #pragma unroll
;                 for (int bj = 0; bj < 2; ++bj) { const size_t o = (size_t)(row0 + EPI_ROWS(ai, m)) * 3072 + col0 + EPI_COL8(bj);
;                     ga[m][bj] = *(const u32x4*)(gate + o + u.seg * 1024); if (u.seg < 2) gb[m][bj] = *(const u32x4*)(gate + o + s1 * 1024); }
; #pragma unroll
;             for (int m = mb; m < mb + 2; ++m) { const int r = row0 + EPI_ROWS(ai, m);
; #pragma unroll
;                 for (int bj = 0; bj < 2; ++bj) {
;                     float g0[8]; unpk8(ga[m][bj], g0);
;                     if (u.seg < 2) { float g1[8]; unpk8(gb[m][bj], g1);
; #pragma unroll
;                         for (int e = 0; e < 8; ++e) g0[e] = g0[e] * __builtin_amdgcn_rcpf(fmaxf(g1[e], 1e-20f)); }
; #pragma unroll
;                     for (int e = 0; e < 4; ++e) { acc[ai][bj][m][0][e] *= g0[e]; acc[ai][bj][m][1][e] *= g0[4 + e]; }
;                     if (u.seg == 2) *(u32x4*)(Y + (size_t)r * 1024 + col0 + EPI_COL8(bj)) = pk8(acc[ai][bj][m][0], acc[ai][bj][m][1]);
	v_lshlrev_b32_e32 v234, 16, v204
	v_and_b32_e32 v235, 0xffff0000, v204
	v_lshlrev_b32_e32 v236, 16, v205
	v_and_b32_e32 v237, 0xffff0000, v205
	v_lshlrev_b32_e32 v238, 16, v206
	v_and_b32_e32 v239, 0xffff0000, v206
	v_lshlrev_b32_e32 v240, 16, v207
	v_and_b32_e32 v241, 0xffff0000, v207
	v_max_f32_e32 v234, 0x1e3ce508, v234
	v_max_f32_e32 v235, 0x1e3ce508, v235
	v_max_f32_e32 v236, 0x1e3ce508, v236
	v_max_f32_e32 v237, 0x1e3ce508, v237
	v_max_f32_e32 v238, 0x1e3ce508, v238
	v_max_f32_e32 v239, 0x1e3ce508, v239
	v_max_f32_e32 v240, 0x1e3ce508, v240
	v_max_f32_e32 v241, 0x1e3ce508, v241
	v_rcp_f32_e32 v234, v234
	v_rcp_f32_e32 v235, v235
	v_rcp_f32_e32 v236, v236
	v_rcp_f32_e32 v237, v237
	v_rcp_f32_e32 v238, v238
	v_rcp_f32_e32 v239, v239
	v_rcp_f32_e32 v240, v240
	v_rcp_f32_e32 v241, v241
	v_lshlrev_b32_e32 v204, 16, v200
	v_and_b32_e32 v205, 0xffff0000, v200
	v_lshlrev_b32_e32 v206, 16, v201
	v_and_b32_e32 v207, 0xffff0000, v201
	v_lshlrev_b32_e32 v200, 16, v202
	v_and_b32_e32 v201, 0xffff0000, v202
	v_lshlrev_b32_e32 v202, 16, v203
	v_and_b32_e32 v203, 0xffff0000, v203
	v_pk_mul_f32 v[204:205], v[234:235], v[204:205]
	v_pk_mul_f32 v[206:207], v[236:237], v[206:207]
	v_pk_mul_f32 v[200:201], v[238:239], v[200:201]
	v_pk_mul_f32 v[202:203], v[240:241], v[202:203]
	v_pk_mul_f32 v[36:37], v[36:37], v[204:205]
	v_pk_mul_f32 v[32:33], v[32:33], v[200:201]
	v_pk_mul_f32 v[38:39], v[38:39], v[206:207]
	v_pk_mul_f32 v[34:35], v[34:35], v[202:203]
	v_lshlrev_b32_e32 v234, 16, v230
	v_and_b32_e32 v235, 0xffff0000, v230
	v_lshlrev_b32_e32 v236, 16, v231
	v_and_b32_e32 v237, 0xffff0000, v231
	v_lshlrev_b32_e32 v238, 16, v232
	v_and_b32_e32 v239, 0xffff0000, v232
	v_lshlrev_b32_e32 v240, 16, v233
	v_and_b32_e32 v241, 0xffff0000, v233
	v_max_f32_e32 v234, 0x1e3ce508, v234
	v_max_f32_e32 v235, 0x1e3ce508, v235
	v_max_f32_e32 v236, 0x1e3ce508, v236
	v_max_f32_e32 v237, 0x1e3ce508, v237
	v_max_f32_e32 v238, 0x1e3ce508, v238
	v_max_f32_e32 v239, 0x1e3ce508, v239
	v_max_f32_e32 v240, 0x1e3ce508, v240
	v_max_f32_e32 v241, 0x1e3ce508, v241
	v_rcp_f32_e32 v234, v234
	v_rcp_f32_e32 v235, v235
	v_rcp_f32_e32 v236, v236
	v_rcp_f32_e32 v237, v237
	v_rcp_f32_e32 v238, v238
	v_rcp_f32_e32 v239, v239
	v_rcp_f32_e32 v240, v240
	v_rcp_f32_e32 v241, v241
	v_lshlrev_b32_e32 v230, 16, v208
	v_and_b32_e32 v231, 0xffff0000, v208
	v_lshlrev_b32_e32 v232, 16, v209
	v_and_b32_e32 v233, 0xffff0000, v209
	v_lshlrev_b32_e32 v208, 16, v210
	v_and_b32_e32 v209, 0xffff0000, v210
	v_lshlrev_b32_e32 v210, 16, v211
	v_and_b32_e32 v211, 0xffff0000, v211
	v_pk_mul_f32 v[230:231], v[234:235], v[230:231]
	v_pk_mul_f32 v[232:233], v[236:237], v[232:233]
	v_pk_mul_f32 v[208:209], v[238:239], v[208:209]
	v_pk_mul_f32 v[210:211], v[240:241], v[210:211]
	v_pk_mul_f32 v[4:5], v[4:5], v[230:231]
	v_pk_mul_f32 v[0:1], v[0:1], v[208:209]
	v_pk_mul_f32 v[6:7], v[6:7], v[232:233]
	v_pk_mul_f32 v[2:3], v[2:3], v[210:211]
	s_branch .LBB0_296
.Lg3e_last:
	s_add_u32 s6, s50, 0x0
	s_addc_u32 s7, s51, 0
	global_load_dwordx4 v[130:133], v214, s[6:7]
	global_load_dwordx4 v[134:137], v214, s[6:7] offset:256
	s_add_u32 s6, s50, 0x18000
	s_addc_u32 s7, s51, 0
	global_load_dwordx4 v[138:141], v214, s[6:7]
	global_load_dwordx4 v[142:145], v214, s[6:7] offset:256
	s_add_u32 s6, s50, 0x30000
	s_addc_u32 s7, s51, 0
	global_load_dwordx4 v[146:149], v214, s[6:7]
	global_load_dwordx4 v[150:153], v214, s[6:7] offset:256
	s_add_u32 s6, s50, 0x48000
	s_addc_u32 s7, s51, 0
	global_load_dwordx4 v[154:157], v214, s[6:7]
	global_load_dwordx4 v[158:161], v214, s[6:7] offset:256
	s_add_u32 s6, s50, 0xc0000
	s_addc_u32 s7, s51, 0
	global_load_dwordx4 v[162:165], v214, s[6:7]
	global_load_dwordx4 v[166:169], v214, s[6:7] offset:256
	s_add_u32 s6, s50, 0xd8000
	s_addc_u32 s7, s51, 0
	global_load_dwordx4 v[170:173], v214, s[6:7]
	global_load_dwordx4 v[174:177], v214, s[6:7] offset:256
	s_add_u32 s6, s50, 0xf0000
	s_addc_u32 s7, s51, 0
	global_load_dwordx4 v[200:203], v214, s[6:7]
	global_load_dwordx4 v[204:207], v214, s[6:7] offset:256
	s_add_u32 s6, s50, 0x108000
	s_addc_u32 s7, s51, 0
	global_load_dwordx4 v[208:211], v214, s[6:7]
	global_load_dwordx4 v[230:233], v214, s[6:7] offset:256
	s_waitcnt vmcnt(14)
	s_add_u32 s8, s42, 0x0
	s_addc_u32 s9, s43, 0
	v_lshlrev_b32_e32 v234, 16, v130
	v_and_b32_e32 v235, 0xffff0000, v130
	v_lshlrev_b32_e32 v236, 16, v131
	v_and_b32_e32 v237, 0xffff0000, v131
	v_lshlrev_b32_e32 v238, 16, v132
	v_and_b32_e32 v239, 0xffff0000, v132
	v_lshlrev_b32_e32 v240, 16, v133
	v_and_b32_e32 v241, 0xffff0000, v133
	v_pk_mul_f32 v[126:127], v[126:127], v[234:235]
	v_pk_mul_f32 v[122:123], v[122:123], v[238:239]
	v_pk_mul_f32 v[128:129], v[128:129], v[236:237]
	v_pk_mul_f32 v[124:125], v[124:125], v[240:241]
	v_cvt_pk_bf16_f32 v130, v126, v127
	v_cvt_pk_bf16_f32 v131, v128, v129
	v_cvt_pk_bf16_f32 v132, v122, v123
	v_cvt_pk_bf16_f32 v133, v124, v125
	global_store_dwordx4 v215, v[130:133], s[8:9]
	v_lshlrev_b32_e32 v234, 16, v134
	v_and_b32_e32 v235, 0xffff0000, v134
	v_lshlrev_b32_e32 v236, 16, v135
	v_and_b32_e32 v237, 0xffff0000, v135
	v_lshlrev_b32_e32 v238, 16, v136
	v_and_b32_e32 v239, 0xffff0000, v136
	v_lshlrev_b32_e32 v240, 16, v137
	v_and_b32_e32 v241, 0xffff0000, v137
	v_pk_mul_f32 v[92:93], v[92:93], v[234:235]
	v_pk_mul_f32 v[88:89], v[88:89], v[238:239]
	v_pk_mul_f32 v[94:95], v[94:95], v[236:237]
	v_pk_mul_f32 v[90:91], v[90:91], v[240:241]
	v_cvt_pk_bf16_f32 v134, v92, v93
	v_cvt_pk_bf16_f32 v135, v94, v95
	v_cvt_pk_bf16_f32 v136, v88, v89
	v_cvt_pk_bf16_f32 v137, v90, v91
	global_store_dwordx4 v215, v[134:137], s[8:9] offset:256
	s_waitcnt vmcnt(14)
; DI u32x4 pk8(const f32x4& a, const f32x4& b) { u32x4 w; w.x = pk2(a[0], a[1]); w.y = pk2(a[2], a[3]); w.z = pk2(b[0], b[1]); w.w = pk2(b[2], b[3]); return w; }
;     DI void operator()(Acc& acc, const Unit& u, int wr, int wc, int fr, int fq) const {
;     ...
;                 for (int bj = 0; bj < 2; ++bj) { const size_t o = (size_t)(row0 + EPI_ROWS(ai, m)) * 3072 + col0 + EPI_COL8(bj);
;                     ga[m][bj] = *(const u32x4*)(gate + o + u.seg * 1024); if (u.seg < 2) gb[m][bj] = *(const u32x4*)(gate + o + s1 * 1024); }
; #pragma unroll
;             for (int m = mb; m < mb + 2; ++m) { const int r = row0 + EPI_ROWS(ai, m);
; #pragma unroll
;                 for (int bj = 0; bj < 2; ++bj) {
;                     float g0[8]; unpk8(ga[m][bj], g0);
;                     if (u.seg < 2) { float g1[8]; unpk8(gb[m][bj], g1);
; #pragma unroll
;                         for (int e = 0; e < 8; ++e) g0[e] = g0[e] * __builtin_amdgcn_rcpf(fmaxf(g1[e], 1e-20f)); }
; #pragma unroll
;                     for (int e = 0; e < 4; ++e) { acc[ai][bj][m][0][e] *= g0[e]; acc[ai][bj][m][1][e] *= g0[4 + e]; }
;                     if (u.seg == 2) *(u32x4*)(Y + (size_t)r * 1024 + col0 + EPI_COL8(bj)) = pk8(acc[ai][bj][m][0], acc[ai][bj][m][1]);
	s_add_u32 s8, s42, 0x8000
	s_addc_u32 s9, s43, 0
	v_lshlrev_b32_e32 v234, 16, v138
	v_and_b32_e32 v235, 0xffff0000, v138
	v_lshlrev_b32_e32 v236, 16, v139
	v_and_b32_e32 v237, 0xffff0000, v139
	v_lshlrev_b32_e32 v238, 16, v140
	v_and_b32_e32 v239, 0xffff0000, v140
	v_lshlrev_b32_e32 v240, 16, v141
	v_and_b32_e32 v241, 0xffff0000, v141
	v_pk_mul_f32 v[118:119], v[118:119], v[234:235]
	v_pk_mul_f32 v[114:115], v[114:115], v[238:239]
	v_pk_mul_f32 v[120:121], v[120:121], v[236:237]
	v_pk_mul_f32 v[116:117], v[116:117], v[240:241]
	v_cvt_pk_bf16_f32 v138, v118, v119
	v_cvt_pk_bf16_f32 v139, v120, v121
	v_cvt_pk_bf16_f32 v140, v114, v115
	v_cvt_pk_bf16_f32 v141, v116, v117
	global_store_dwordx4 v215, v[138:141], s[8:9]
	v_lshlrev_b32_e32 v234, 16, v142
	v_and_b32_e32 v235, 0xffff0000, v142
	v_lshlrev_b32_e32 v236, 16, v143
	v_and_b32_e32 v237, 0xffff0000, v143
	v_lshlrev_b32_e32 v238, 16, v144
	v_and_b32_e32 v239, 0xffff0000, v144
	v_lshlrev_b32_e32 v240, 16, v145
	v_and_b32_e32 v241, 0xffff0000, v145
	v_pk_mul_f32 v[84:85], v[84:85], v[234:235]
	v_pk_mul_f32 v[80:81], v[80:81], v[238:239]
	v_pk_mul_f32 v[86:87], v[86:87], v[236:237]
	v_pk_mul_f32 v[82:83], v[82:83], v[240:241]
	v_cvt_pk_bf16_f32 v142, v84, v85
	v_cvt_pk_bf16_f32 v143, v86, v87
	v_cvt_pk_bf16_f32 v144, v80, v81
	v_cvt_pk_bf16_f32 v145, v82, v83
	global_store_dwordx4 v215, v[142:145], s[8:9] offset:256
	s_waitcnt vmcnt(14)
	s_add_u32 s8, s42, 0x10000
	s_addc_u32 s9, s43, 0
	v_lshlrev_b32_e32 v234, 16, v146
	v_and_b32_e32 v235, 0xffff0000, v146
	v_lshlrev_b32_e32 v236, 16, v147
	v_and_b32_e32 v237, 0xffff0000, v147
	v_lshlrev_b32_e32 v238, 16, v148
	v_and_b32_e32 v239, 0xffff0000, v148
	v_lshlrev_b32_e32 v240, 16, v149
	v_and_b32_e32 v241, 0xffff0000, v149
	v_pk_mul_f32 v[110:111], v[110:111], v[234:235]
	v_pk_mul_f32 v[106:107], v[106:107], v[238:239]
	v_pk_mul_f32 v[112:113], v[112:113], v[236:237]
	v_pk_mul_f32 v[108:109], v[108:109], v[240:241]
	v_cvt_pk_bf16_f32 v146, v110, v111
	v_cvt_pk_bf16_f32 v147, v112, v113
	v_cvt_pk_bf16_f32 v148, v106, v107
	v_cvt_pk_bf16_f32 v149, v108, v109
	global_store_dwordx4 v215, v[146:149], s[8:9]
	v_lshlrev_b32_e32 v234, 16, v150
	v_and_b32_e32 v235, 0xffff0000, v150
	v_lshlrev_b32_e32 v236, 16, v151
	v_and_b32_e32 v237, 0xffff0000, v151
	v_lshlrev_b32_e32 v238, 16, v152
	v_and_b32_e32 v239, 0xffff0000, v152
	v_lshlrev_b32_e32 v240, 16, v153
	v_and_b32_e32 v241, 0xffff0000, v153
	v_pk_mul_f32 v[76:77], v[76:77], v[234:235]
	v_pk_mul_f32 v[72:73], v[72:73], v[238:239]
	v_pk_mul_f32 v[78:79], v[78:79], v[236:237]
	v_pk_mul_f32 v[74:75], v[74:75], v[240:241]
	v_cvt_pk_bf16_f32 v150, v76, v77
	v_cvt_pk_bf16_f32 v151, v78, v79
	v_cvt_pk_bf16_f32 v152, v72, v73
	v_cvt_pk_bf16_f32 v153, v74, v75
	global_store_dwordx4 v215, v[150:153], s[8:9] offset:256
	s_waitcnt vmcnt(14)
	s_add_u32 s8, s42, 0x18000
	s_addc_u32 s9, s43, 0
	v_lshlrev_b32_e32 v234, 16, v154
	v_and_b32_e32 v235, 0xffff0000, v154
	v_lshlrev_b32_e32 v236, 16, v155
	v_and_b32_e32 v237, 0xffff0000, v155
	v_lshlrev_b32_e32 v238, 16, v156
	v_and_b32_e32 v239, 0xffff0000, v156
	v_lshlrev_b32_e32 v240, 16, v157
	v_and_b32_e32 v241, 0xffff0000, v157
	v_pk_mul_f32 v[102:103], v[102:103], v[234:235]
	v_pk_mul_f32 v[98:99], v[98:99], v[238:239]
	v_pk_mul_f32 v[104:105], v[104:105], v[236:237]
	v_pk_mul_f32 v[100:101], v[100:101], v[240:241]
	v_cvt_pk_bf16_f32 v154, v102, v103
	v_cvt_pk_bf16_f32 v155, v104, v105
	v_cvt_pk_bf16_f32 v156, v98, v99
	v_cvt_pk_bf16_f32 v157, v100, v101
	global_store_dwordx4 v215, v[154:157], s[8:9]
	v_lshlrev_b32_e32 v234, 16, v158
	v_and_b32_e32 v235, 0xffff0000, v158
	v_lshlrev_b32_e32 v236, 16, v159
	v_and_b32_e32 v237, 0xffff0000, v159
	v_lshlrev_b32_e32 v238, 16, v160
	v_and_b32_e32 v239, 0xffff0000, v160
	v_lshlrev_b32_e32 v240, 16, v161
	v_and_b32_e32 v241, 0xffff0000, v161
	v_pk_mul_f32 v[68:69], v[68:69], v[234:235]
	v_pk_mul_f32 v[64:65], v[64:65], v[238:239]
	v_pk_mul_f32 v[70:71], v[70:71], v[236:237]
	v_pk_mul_f32 v[66:67], v[66:67], v[240:241]
	v_cvt_pk_bf16_f32 v158, v68, v69
	v_cvt_pk_bf16_f32 v159, v70, v71
	v_cvt_pk_bf16_f32 v160, v64, v65
	v_cvt_pk_bf16_f32 v161, v66, v67
	global_store_dwordx4 v215, v[158:161], s[8:9] offset:256
	s_waitcnt vmcnt(14)
; DI u32x4 pk8(const f32x4& a, const f32x4& b) { u32x4 w; w.x = pk2(a[0], a[1]); w.y = pk2(a[2], a[3]); w.z = pk2(b[0], b[1]); w.w = pk2(b[2], b[3]); return w; }
;     DI void operator()(Acc& acc, const Unit& u, int wr, int wc, int fr, int fq) const {
;     ...
;                 for (int bj = 0; bj < 2; ++bj) { const size_t o = (size_t)(row0 + EPI_ROWS(ai, m)) * 3072 + col0 + EPI_COL8(bj);
;                     ga[m][bj] = *(const u32x4*)(gate + o + u.seg * 1024); if (u.seg < 2) gb[m][bj] = *(const u32x4*)(gate + o + s1 * 1024); }
; #pragma unroll
;             for (int m = mb; m < mb + 2; ++m) { const int r = row0 + EPI_ROWS(ai, m);
; #pragma unroll
;                 for (int bj = 0; bj < 2; ++bj) {
;                     float g0[8]; unpk8(ga[m][bj], g0);
;                     if (u.seg < 2) { float g1[8]; unpk8(gb[m][bj], g1);
; #pragma unroll
;                         for (int e = 0; e < 8; ++e) g0[e] = g0[e] * __builtin_amdgcn_rcpf(fmaxf(g1[e], 1e-20f)); }
; #pragma unroll
;                     for (int e = 0; e < 4; ++e) { acc[ai][bj][m][0][e] *= g0[e]; acc[ai][bj][m][1][e] *= g0[4 + e]; }
;                     if (u.seg == 2) *(u32x4*)(Y + (size_t)r * 1024 + col0 + EPI_COL8(bj)) = pk8(acc[ai][bj][m][0], acc[ai][bj][m][1]);
	s_add_u32 s8, s42, 0x40000
	s_addc_u32 s9, s43, 0
	v_lshlrev_b32_e32 v234, 16, v162
	v_and_b32_e32 v235, 0xffff0000, v162
	v_lshlrev_b32_e32 v236, 16, v163
	v_and_b32_e32 v237, 0xffff0000, v163
	v_lshlrev_b32_e32 v238, 16, v164
	v_and_b32_e32 v239, 0xffff0000, v164
	v_lshlrev_b32_e32 v240, 16, v165
	v_and_b32_e32 v241, 0xffff0000, v165
	v_pk_mul_f32 v[60:61], v[60:61], v[234:235]
	v_pk_mul_f32 v[56:57], v[56:57], v[238:239]
	v_pk_mul_f32 v[62:63], v[62:63], v[236:237]
	v_pk_mul_f32 v[58:59], v[58:59], v[240:241]
	v_cvt_pk_bf16_f32 v162, v60, v61
	v_cvt_pk_bf16_f32 v163, v62, v63
	v_cvt_pk_bf16_f32 v164, v56, v57
	v_cvt_pk_bf16_f32 v165, v58, v59
	global_store_dwordx4 v215, v[162:165], s[8:9]
	v_lshlrev_b32_e32 v234, 16, v166
	v_and_b32_e32 v235, 0xffff0000, v166
	v_lshlrev_b32_e32 v236, 16, v167
	v_and_b32_e32 v237, 0xffff0000, v167
	v_lshlrev_b32_e32 v238, 16, v168
	v_and_b32_e32 v239, 0xffff0000, v168
	v_lshlrev_b32_e32 v240, 16, v169
	v_and_b32_e32 v241, 0xffff0000, v169
	v_pk_mul_f32 v[28:29], v[28:29], v[234:235]
	v_pk_mul_f32 v[24:25], v[24:25], v[238:239]
	v_pk_mul_f32 v[30:31], v[30:31], v[236:237]
	v_pk_mul_f32 v[26:27], v[26:27], v[240:241]
	v_cvt_pk_bf16_f32 v166, v28, v29
	v_cvt_pk_bf16_f32 v167, v30, v31
	v_cvt_pk_bf16_f32 v168, v24, v25
	v_cvt_pk_bf16_f32 v169, v26, v27
	global_store_dwordx4 v215, v[166:169], s[8:9] offset:256
	s_waitcnt vmcnt(14)
	s_add_u32 s8, s42, 0x48000
	s_addc_u32 s9, s43, 0
	v_lshlrev_b32_e32 v234, 16, v170
	v_and_b32_e32 v235, 0xffff0000, v170
	v_lshlrev_b32_e32 v236, 16, v171
	v_and_b32_e32 v237, 0xffff0000, v171
	v_lshlrev_b32_e32 v238, 16, v172
	v_and_b32_e32 v239, 0xffff0000, v172
	v_lshlrev_b32_e32 v240, 16, v173
	v_and_b32_e32 v241, 0xffff0000, v173
	v_pk_mul_f32 v[52:53], v[52:53], v[234:235]
	v_pk_mul_f32 v[48:49], v[48:49], v[238:239]
	v_pk_mul_f32 v[54:55], v[54:55], v[236:237]
	v_pk_mul_f32 v[50:51], v[50:51], v[240:241]
	v_cvt_pk_bf16_f32 v170, v52, v53
	v_cvt_pk_bf16_f32 v171, v54, v55
	v_cvt_pk_bf16_f32 v172, v48, v49
	v_cvt_pk_bf16_f32 v173, v50, v51
	global_store_dwordx4 v215, v[170:173], s[8:9]
	v_lshlrev_b32_e32 v234, 16, v174
	v_and_b32_e32 v235, 0xffff0000, v174
	v_lshlrev_b32_e32 v236, 16, v175
	v_and_b32_e32 v237, 0xffff0000, v175
	v_lshlrev_b32_e32 v238, 16, v176
	v_and_b32_e32 v239, 0xffff0000, v176
	v_lshlrev_b32_e32 v240, 16, v177
	v_and_b32_e32 v241, 0xffff0000, v177
	v_pk_mul_f32 v[20:21], v[20:21], v[234:235]
	v_pk_mul_f32 v[16:17], v[16:17], v[238:239]
	v_pk_mul_f32 v[22:23], v[22:23], v[236:237]
	v_pk_mul_f32 v[18:19], v[18:19], v[240:241]
	v_cvt_pk_bf16_f32 v174, v20, v21
	v_cvt_pk_bf16_f32 v175, v22, v23
	v_cvt_pk_bf16_f32 v176, v16, v17
	v_cvt_pk_bf16_f32 v177, v18, v19
	global_store_dwordx4 v215, v[174:177], s[8:9] offset:256
	s_waitcnt vmcnt(14)
	s_add_u32 s8, s42, 0x50000
	s_addc_u32 s9, s43, 0
	v_lshlrev_b32_e32 v234, 16, v200
	v_and_b32_e32 v235, 0xffff0000, v200
	v_lshlrev_b32_e32 v236, 16, v201
	v_and_b32_e32 v237, 0xffff0000, v201
	v_lshlrev_b32_e32 v238, 16, v202
	v_and_b32_e32 v239, 0xffff0000, v202
	v_lshlrev_b32_e32 v240, 16, v203
	v_and_b32_e32 v241, 0xffff0000, v203
	v_pk_mul_f32 v[44:45], v[44:45], v[234:235]
	v_pk_mul_f32 v[40:41], v[40:41], v[238:239]
	v_pk_mul_f32 v[46:47], v[46:47], v[236:237]
	v_pk_mul_f32 v[42:43], v[42:43], v[240:241]
	v_cvt_pk_bf16_f32 v200, v44, v45
	v_cvt_pk_bf16_f32 v201, v46, v47
	v_cvt_pk_bf16_f32 v202, v40, v41
	v_cvt_pk_bf16_f32 v203, v42, v43
	global_store_dwordx4 v215, v[200:203], s[8:9]
	v_lshlrev_b32_e32 v234, 16, v204
	v_and_b32_e32 v235, 0xffff0000, v204
	v_lshlrev_b32_e32 v236, 16, v205
	v_and_b32_e32 v237, 0xffff0000, v205
	v_lshlrev_b32_e32 v238, 16, v206
	v_and_b32_e32 v239, 0xffff0000, v206
	v_lshlrev_b32_e32 v240, 16, v207
	v_and_b32_e32 v241, 0xffff0000, v207
	v_pk_mul_f32 v[12:13], v[12:13], v[234:235]
	v_pk_mul_f32 v[8:9], v[8:9], v[238:239]
	v_pk_mul_f32 v[14:15], v[14:15], v[236:237]
	v_pk_mul_f32 v[10:11], v[10:11], v[240:241]
	v_cvt_pk_bf16_f32 v204, v12, v13
	v_cvt_pk_bf16_f32 v205, v14, v15
	v_cvt_pk_bf16_f32 v206, v8, v9
	v_cvt_pk_bf16_f32 v207, v10, v11
	global_store_dwordx4 v215, v[204:207], s[8:9] offset:256
	s_waitcnt vmcnt(14)
	s_add_u32 s8, s42, 0x58000
	s_addc_u32 s9, s43, 0
	v_lshlrev_b32_e32 v234, 16, v208
	v_and_b32_e32 v235, 0xffff0000, v208
	v_lshlrev_b32_e32 v236, 16, v209
	v_and_b32_e32 v237, 0xffff0000, v209
	v_lshlrev_b32_e32 v238, 16, v210
	v_and_b32_e32 v239, 0xffff0000, v210
	v_lshlrev_b32_e32 v240, 16, v211
	v_and_b32_e32 v241, 0xffff0000, v211
	v_pk_mul_f32 v[36:37], v[36:37], v[234:235]
	v_pk_mul_f32 v[32:33], v[32:33], v[238:239]
	v_pk_mul_f32 v[38:39], v[38:39], v[236:237]
	v_pk_mul_f32 v[34:35], v[34:35], v[240:241]
	v_cvt_pk_bf16_f32 v208, v36, v37
	v_cvt_pk_bf16_f32 v209, v38, v39
	v_cvt_pk_bf16_f32 v210, v32, v33
	v_cvt_pk_bf16_f32 v211, v34, v35
	global_store_dwordx4 v215, v[208:211], s[8:9]
	v_lshlrev_b32_e32 v234, 16, v230
	v_and_b32_e32 v235, 0xffff0000, v230
	v_lshlrev_b32_e32 v236, 16, v231
	v_and_b32_e32 v237, 0xffff0000, v231
	v_lshlrev_b32_e32 v238, 16, v232
	v_and_b32_e32 v239, 0xffff0000, v232
	v_lshlrev_b32_e32 v240, 16, v233
	v_and_b32_e32 v241, 0xffff0000, v233
	v_pk_mul_f32 v[4:5], v[4:5], v[234:235]
	v_pk_mul_f32 v[0:1], v[0:1], v[238:239]
	v_pk_mul_f32 v[6:7], v[6:7], v[236:237]
	v_pk_mul_f32 v[2:3], v[2:3], v[240:241]
	v_cvt_pk_bf16_f32 v230, v4, v5
	v_cvt_pk_bf16_f32 v231, v6, v7
	v_cvt_pk_bf16_f32 v232, v0, v1
	v_cvt_pk_bf16_f32 v233, v2, v3
	global_store_dwordx4 v215, v[230:233], s[8:9] offset:256
